# hand-written M2 state scan: a thread's 32 chunk-state loads issued together (the compiled loop fetched one chunk at a time), decay factors via one load + readlanes, stores after the scan
# speedup vs baseline: 1.0045x; 1.0006x over previous
; DI unsigned pk2(float lo, float hi) { const f32x2_t v = {lo, hi}; const bf16x2_t b = __builtin_convertvector(v, bf16x2_t); return __builtin_bit_cast(unsigned, b); }
; __global__ void __launch_bounds__(512, 2) fwd_megakernel(Args args) {
;     ...
;             for (int e = bid * 512 + tid; e < BATCH * 8 * 2048; e += G * 512) {
;                 const int i4 = e & 2047, h = (e >> 11) & 7, b = e >> 14;
;                 f32x4 carry = (f32x4){0.f, 0.f, 0.f, 0.f};
; #pragma unroll 8
;                 for (int c = 0; c < NCH; ++c) {
;                     const int unit = (b * NCH + c) * 8 + h;
;                     const f32x4 st = *(const f32x4*)(ST + (size_t)unit * 8192 + i4 * 4); const float dec = CD[((b * NCH + c) * 2 + (h >> 2)) * 32 + (h & 3)];
;                     u32x2 w; w.x = pk2(carry.x, carry.y); w.y = pk2(carry.z, carry.w); *(u32x2*)(PV + (size_t)unit * 8192 + i4 * 4) = w;
;                     carry = carry * dec + st;
.LBB0_867:
	s_or_b64 exec, exec, s[4:5]
	v_readlane_b32 s2, v251, 0
	s_and_b32 s3, s2, 7
	s_lshl_b32 s3, s3, 5
	s_lshr_b32 s2, s2, 3
	s_add_i32 s2, s2, s3
	s_lshl_b32 s2, s2, 9
	s_waitcnt lgkmcnt(0)
	s_barrier
	s_lshr_b32 s3, s2, 9
	s_and_b32 s4, s3, 3
	s_lshl_b32 s4, s4, 9
	s_bfe_u32 s5, s3, 0x30002
	s_lshr_b32 s6, s3, 5
	s_lshl_b32 s7, s6, 8
	s_add_i32 s7, s7, s5
	v_readlane_b32 s8, v251, 7
	v_readlane_b32 s9, v251, 8
	s_lshl_b32 s10, s7, 15
	s_add_u32 s8, s8, s10
	s_addc_u32 s9, s9, 0
	v_readlane_b32 s10, v252, 7
	v_readlane_b32 s11, v252, 8
	s_lshl_b32 s12, s7, 14
	s_add_u32 s10, s10, s12
	s_addc_u32 s11, s11, 0
	s_lshl_b32 s12, s6, 11
	s_lshr_b32 s13, s5, 2
	s_lshl_b32 s13, s13, 5
	s_add_i32 s12, s12, s13
	s_and_b32 s13, s5, 3
	s_add_i32 s12, s12, s13
	s_lshl_b32 s12, s12, 2
	s_add_u32 s12, s80, s12
	s_addc_u32 s13, s81, 0
	v_add_u32_e32 v238, s4, v195
	v_lshlrev_b32_e32 v239, 3, v238
	v_lshlrev_b32_e32 v238, 4, v238
	v_and_b32_e32 v243, 31, v195
	v_lshlrev_b32_e32 v243, 8, v243
	global_load_dword v248, v243, s[12:13]
	global_load_dwordx4 v[116:119], v238, s[8:9]
	s_add_u32 s8, s8, 0x40000
	s_addc_u32 s9, s9, 0
	global_load_dwordx4 v[120:123], v238, s[8:9]
	s_add_u32 s8, s8, 0x40000
	s_addc_u32 s9, s9, 0
	global_load_dwordx4 v[124:127], v238, s[8:9]
	s_add_u32 s8, s8, 0x40000
	s_addc_u32 s9, s9, 0
	global_load_dwordx4 v[128:131], v238, s[8:9]
	s_add_u32 s8, s8, 0x40000
	s_addc_u32 s9, s9, 0
	global_load_dwordx4 v[132:135], v238, s[8:9]
	s_add_u32 s8, s8, 0x40000
	s_addc_u32 s9, s9, 0
	global_load_dwordx4 v[136:139], v238, s[8:9]
	s_add_u32 s8, s8, 0x40000
	s_addc_u32 s9, s9, 0
	global_load_dwordx4 v[140:143], v238, s[8:9]
	s_add_u32 s8, s8, 0x40000
	s_addc_u32 s9, s9, 0
	global_load_dwordx4 v[144:147], v238, s[8:9]
	s_add_u32 s8, s8, 0x40000
	s_addc_u32 s9, s9, 0
	global_load_dwordx4 v[148:151], v238, s[8:9]
	s_add_u32 s8, s8, 0x40000
	s_addc_u32 s9, s9, 0
	global_load_dwordx4 v[152:155], v238, s[8:9]
	s_add_u32 s8, s8, 0x40000
	s_addc_u32 s9, s9, 0
	global_load_dwordx4 v[156:159], v238, s[8:9]
	s_add_u32 s8, s8, 0x40000
	s_addc_u32 s9, s9, 0
	global_load_dwordx4 v[160:163], v238, s[8:9]
	s_add_u32 s8, s8, 0x40000
	s_addc_u32 s9, s9, 0
	global_load_dwordx4 v[164:167], v238, s[8:9]
	s_add_u32 s8, s8, 0x40000
	s_addc_u32 s9, s9, 0
	global_load_dwordx4 v[168:171], v238, s[8:9]
	s_add_u32 s8, s8, 0x40000
	s_addc_u32 s9, s9, 0
	global_load_dwordx4 v[172:175], v238, s[8:9]
	s_add_u32 s8, s8, 0x40000
	s_addc_u32 s9, s9, 0
	global_load_dwordx4 v[176:179], v238, s[8:9]
	s_add_u32 s8, s8, 0x40000
	s_addc_u32 s9, s9, 0
	global_load_dwordx4 v[180:183], v238, s[8:9]
	s_add_u32 s8, s8, 0x40000
	s_addc_u32 s9, s9, 0
	global_load_dwordx4 v[184:187], v238, s[8:9]
	s_add_u32 s8, s8, 0x40000
	s_addc_u32 s9, s9, 0
	global_load_dwordx4 v[188:191], v238, s[8:9]
	s_add_u32 s8, s8, 0x40000
	s_addc_u32 s9, s9, 0
	global_load_dwordx4 v[0:3], v238, s[8:9]
	s_add_u32 s8, s8, 0x40000
	s_addc_u32 s9, s9, 0
	global_load_dwordx4 v[4:7], v238, s[8:9]
	s_add_u32 s8, s8, 0x40000
	s_addc_u32 s9, s9, 0
	global_load_dwordx4 v[8:11], v238, s[8:9]
	s_add_u32 s8, s8, 0x40000
	s_addc_u32 s9, s9, 0
	global_load_dwordx4 v[12:15], v238, s[8:9]
	s_add_u32 s8, s8, 0x40000
	s_addc_u32 s9, s9, 0
	global_load_dwordx4 v[16:19], v238, s[8:9]
	s_add_u32 s8, s8, 0x40000
	s_addc_u32 s9, s9, 0
	global_load_dwordx4 v[20:23], v238, s[8:9]
	s_add_u32 s8, s8, 0x40000
	s_addc_u32 s9, s9, 0
	global_load_dwordx4 v[196:199], v238, s[8:9]
	s_add_u32 s8, s8, 0x40000
	s_addc_u32 s9, s9, 0
	global_load_dwordx4 v[202:205], v238, s[8:9]
	s_add_u32 s8, s8, 0x40000
	s_addc_u32 s9, s9, 0
	global_load_dwordx4 v[206:209], v238, s[8:9]
	s_add_u32 s8, s8, 0x40000
	s_addc_u32 s9, s9, 0
	global_load_dwordx4 v[210:213], v238, s[8:9]
	s_add_u32 s8, s8, 0x40000
	s_addc_u32 s9, s9, 0
	global_load_dwordx4 v[230:233], v238, s[8:9]
	s_add_u32 s8, s8, 0x40000
	s_addc_u32 s9, s9, 0
	global_load_dwordx4 v[234:237], v238, s[8:9]
	s_add_u32 s8, s8, 0x40000
	s_addc_u32 s9, s9, 0
	global_load_dwordx4 v[244:247], v238, s[8:9]
	v_mov_b32_e32 v214, 0
	v_mov_b32_e32 v215, 0
	s_waitcnt vmcnt(32)
	v_readlane_b32 s28, v248, 0
	v_readlane_b32 s29, v248, 1
	v_readlane_b32 s30, v248, 2
	v_readlane_b32 s31, v248, 3
	v_readlane_b32 s33, v248, 4
	v_readlane_b32 s34, v248, 5
	v_readlane_b32 s35, v248, 6
	v_readlane_b32 s36, v248, 7
	v_readlane_b32 s37, v248, 8
	v_readlane_b32 s38, v248, 9
	v_readlane_b32 s39, v248, 10
	v_readlane_b32 s40, v248, 11
	v_readlane_b32 s41, v248, 12
	v_readlane_b32 s42, v248, 13
	v_readlane_b32 s43, v248, 14
	v_readlane_b32 s46, v248, 15
	v_readlane_b32 s47, v248, 16
	v_readlane_b32 s48, v248, 17
	v_readlane_b32 s49, v248, 18
	v_readlane_b32 s50, v248, 19
	v_readlane_b32 s51, v248, 20
	v_readlane_b32 s52, v248, 21
	v_readlane_b32 s53, v248, 22
	v_readlane_b32 s55, v248, 23
	v_readlane_b32 s56, v248, 24
	v_readlane_b32 s57, v248, 25
	v_readlane_b32 s58, v248, 26
	v_readlane_b32 s60, v248, 27
	v_readlane_b32 s61, v248, 28
	v_readlane_b32 s62, v248, 29
	v_readlane_b32 s63, v248, 30
	v_readlane_b32 s64, v248, 31
	s_waitcnt vmcnt(31)
	s_waitcnt vmcnt(30)
	v_fma_f32 v120, v116, s29, v120
	v_fma_f32 v121, v117, s29, v121
	v_fma_f32 v122, v118, s29, v122
	v_fma_f32 v123, v119, s29, v123
	v_cvt_pk_bf16_f32 v116, v116, v117
	v_cvt_pk_bf16_f32 v117, v118, v119
	s_waitcnt vmcnt(29)
	v_fma_f32 v124, v120, s30, v124
	v_fma_f32 v125, v121, s30, v125
	v_fma_f32 v126, v122, s30, v126
	v_fma_f32 v127, v123, s30, v127
	v_cvt_pk_bf16_f32 v120, v120, v121
	v_cvt_pk_bf16_f32 v121, v122, v123
	s_waitcnt vmcnt(28)
	v_fma_f32 v128, v124, s31, v128
	v_fma_f32 v129, v125, s31, v129
	v_fma_f32 v130, v126, s31, v130
	v_fma_f32 v131, v127, s31, v131
	v_cvt_pk_bf16_f32 v124, v124, v125
	v_cvt_pk_bf16_f32 v125, v126, v127
	s_waitcnt vmcnt(27)
; DI unsigned pk2(float lo, float hi) { const f32x2_t v = {lo, hi}; const bf16x2_t b = __builtin_convertvector(v, bf16x2_t); return __builtin_bit_cast(unsigned, b); }
; __global__ void __launch_bounds__(512, 2) fwd_megakernel(Args args) {
;     ...
;                 for (int c = 0; c < NCH; ++c) {
;                     const int unit = (b * NCH + c) * 8 + h;
;                     const f32x4 st = *(const f32x4*)(ST + (size_t)unit * 8192 + i4 * 4); const float dec = CD[((b * NCH + c) * 2 + (h >> 2)) * 32 + (h & 3)];
;                     u32x2 w; w.x = pk2(carry.x, carry.y); w.y = pk2(carry.z, carry.w); *(u32x2*)(PV + (size_t)unit * 8192 + i4 * 4) = w;
;                     carry = carry * dec + st;
	v_fma_f32 v132, v128, s33, v132
	v_fma_f32 v133, v129, s33, v133
	v_fma_f32 v134, v130, s33, v134
	v_fma_f32 v135, v131, s33, v135
	v_cvt_pk_bf16_f32 v128, v128, v129
	v_cvt_pk_bf16_f32 v129, v130, v131
	s_waitcnt vmcnt(26)
	v_fma_f32 v136, v132, s34, v136
	v_fma_f32 v137, v133, s34, v137
	v_fma_f32 v138, v134, s34, v138
	v_fma_f32 v139, v135, s34, v139
	v_cvt_pk_bf16_f32 v132, v132, v133
	v_cvt_pk_bf16_f32 v133, v134, v135
	s_waitcnt vmcnt(25)
	v_fma_f32 v140, v136, s35, v140
	v_fma_f32 v141, v137, s35, v141
	v_fma_f32 v142, v138, s35, v142
	v_fma_f32 v143, v139, s35, v143
	v_cvt_pk_bf16_f32 v136, v136, v137
	v_cvt_pk_bf16_f32 v137, v138, v139
	s_waitcnt vmcnt(24)
	v_fma_f32 v144, v140, s36, v144
	v_fma_f32 v145, v141, s36, v145
	v_fma_f32 v146, v142, s36, v146
	v_fma_f32 v147, v143, s36, v147
	v_cvt_pk_bf16_f32 v140, v140, v141
	v_cvt_pk_bf16_f32 v141, v142, v143
	s_waitcnt vmcnt(23)
	v_fma_f32 v148, v144, s37, v148
	v_fma_f32 v149, v145, s37, v149
	v_fma_f32 v150, v146, s37, v150
	v_fma_f32 v151, v147, s37, v151
	v_cvt_pk_bf16_f32 v144, v144, v145
	v_cvt_pk_bf16_f32 v145, v146, v147
	s_waitcnt vmcnt(22)
	v_fma_f32 v152, v148, s38, v152
	v_fma_f32 v153, v149, s38, v153
	v_fma_f32 v154, v150, s38, v154
	v_fma_f32 v155, v151, s38, v155
	v_cvt_pk_bf16_f32 v148, v148, v149
	v_cvt_pk_bf16_f32 v149, v150, v151
	s_waitcnt vmcnt(21)
	v_fma_f32 v156, v152, s39, v156
	v_fma_f32 v157, v153, s39, v157
	v_fma_f32 v158, v154, s39, v158
	v_fma_f32 v159, v155, s39, v159
	v_cvt_pk_bf16_f32 v152, v152, v153
	v_cvt_pk_bf16_f32 v153, v154, v155
	s_waitcnt vmcnt(20)
	v_fma_f32 v160, v156, s40, v160
	v_fma_f32 v161, v157, s40, v161
	v_fma_f32 v162, v158, s40, v162
	v_fma_f32 v163, v159, s40, v163
	v_cvt_pk_bf16_f32 v156, v156, v157
	v_cvt_pk_bf16_f32 v157, v158, v159
	s_waitcnt vmcnt(19)
	v_fma_f32 v164, v160, s41, v164
	v_fma_f32 v165, v161, s41, v165
	v_fma_f32 v166, v162, s41, v166
	v_fma_f32 v167, v163, s41, v167
	v_cvt_pk_bf16_f32 v160, v160, v161
	v_cvt_pk_bf16_f32 v161, v162, v163
	s_waitcnt vmcnt(18)
	v_fma_f32 v168, v164, s42, v168
	v_fma_f32 v169, v165, s42, v169
	v_fma_f32 v170, v166, s42, v170
	v_fma_f32 v171, v167, s42, v171
	v_cvt_pk_bf16_f32 v164, v164, v165
	v_cvt_pk_bf16_f32 v165, v166, v167
	s_waitcnt vmcnt(17)
	v_fma_f32 v172, v168, s43, v172
	v_fma_f32 v173, v169, s43, v173
	v_fma_f32 v174, v170, s43, v174
	v_fma_f32 v175, v171, s43, v175
	v_cvt_pk_bf16_f32 v168, v168, v169
	v_cvt_pk_bf16_f32 v169, v170, v171
	s_waitcnt vmcnt(16)
	v_fma_f32 v176, v172, s46, v176
	v_fma_f32 v177, v173, s46, v177
	v_fma_f32 v178, v174, s46, v178
	v_fma_f32 v179, v175, s46, v179
	v_cvt_pk_bf16_f32 v172, v172, v173
	v_cvt_pk_bf16_f32 v173, v174, v175
	s_waitcnt vmcnt(15)
	v_fma_f32 v180, v176, s47, v180
	v_fma_f32 v181, v177, s47, v181
	v_fma_f32 v182, v178, s47, v182
	v_fma_f32 v183, v179, s47, v183
	v_cvt_pk_bf16_f32 v176, v176, v177
	v_cvt_pk_bf16_f32 v177, v178, v179
	s_waitcnt vmcnt(14)
	v_fma_f32 v184, v180, s48, v184
	v_fma_f32 v185, v181, s48, v185
	v_fma_f32 v186, v182, s48, v186
	v_fma_f32 v187, v183, s48, v187
	v_cvt_pk_bf16_f32 v180, v180, v181
	v_cvt_pk_bf16_f32 v181, v182, v183
	s_waitcnt vmcnt(13)
	v_fma_f32 v188, v184, s49, v188
	v_fma_f32 v189, v185, s49, v189
	v_fma_f32 v190, v186, s49, v190
	v_fma_f32 v191, v187, s49, v191
	v_cvt_pk_bf16_f32 v184, v184, v185
	v_cvt_pk_bf16_f32 v185, v186, v187
	s_waitcnt vmcnt(12)
	v_fma_f32 v0, v188, s50, v0
	v_fma_f32 v1, v189, s50, v1
	v_fma_f32 v2, v190, s50, v2
	v_fma_f32 v3, v191, s50, v3
	v_cvt_pk_bf16_f32 v188, v188, v189
	v_cvt_pk_bf16_f32 v189, v190, v191
	s_waitcnt vmcnt(11)
	v_fma_f32 v4, v0, s51, v4
	v_fma_f32 v5, v1, s51, v5
	v_fma_f32 v6, v2, s51, v6
	v_fma_f32 v7, v3, s51, v7
	v_cvt_pk_bf16_f32 v0, v0, v1
	v_cvt_pk_bf16_f32 v1, v2, v3
	s_waitcnt vmcnt(10)
	v_fma_f32 v8, v4, s52, v8
	v_fma_f32 v9, v5, s52, v9
	v_fma_f32 v10, v6, s52, v10
	v_fma_f32 v11, v7, s52, v11
	v_cvt_pk_bf16_f32 v4, v4, v5
	v_cvt_pk_bf16_f32 v5, v6, v7
	s_waitcnt vmcnt(9)
	v_fma_f32 v12, v8, s53, v12
	v_fma_f32 v13, v9, s53, v13
	v_fma_f32 v14, v10, s53, v14
	v_fma_f32 v15, v11, s53, v15
	v_cvt_pk_bf16_f32 v8, v8, v9
	v_cvt_pk_bf16_f32 v9, v10, v11
	s_waitcnt vmcnt(8)
	v_fma_f32 v16, v12, s55, v16
	v_fma_f32 v17, v13, s55, v17
	v_fma_f32 v18, v14, s55, v18
	v_fma_f32 v19, v15, s55, v19
	v_cvt_pk_bf16_f32 v12, v12, v13
	v_cvt_pk_bf16_f32 v13, v14, v15
	s_waitcnt vmcnt(7)
	v_fma_f32 v20, v16, s56, v20
	v_fma_f32 v21, v17, s56, v21
	v_fma_f32 v22, v18, s56, v22
	v_fma_f32 v23, v19, s56, v23
	v_cvt_pk_bf16_f32 v16, v16, v17
	v_cvt_pk_bf16_f32 v17, v18, v19
	s_waitcnt vmcnt(6)
; DI unsigned pk2(float lo, float hi) { const f32x2_t v = {lo, hi}; const bf16x2_t b = __builtin_convertvector(v, bf16x2_t); return __builtin_bit_cast(unsigned, b); }
; __global__ void __launch_bounds__(512, 2) fwd_megakernel(Args args) {
;     ...
;                 for (int c = 0; c < NCH; ++c) {
;                     const int unit = (b * NCH + c) * 8 + h;
;                     const f32x4 st = *(const f32x4*)(ST + (size_t)unit * 8192 + i4 * 4); const float dec = CD[((b * NCH + c) * 2 + (h >> 2)) * 32 + (h & 3)];
;                     u32x2 w; w.x = pk2(carry.x, carry.y); w.y = pk2(carry.z, carry.w); *(u32x2*)(PV + (size_t)unit * 8192 + i4 * 4) = w;
;                     carry = carry * dec + st;
	v_fma_f32 v196, v20, s57, v196
	v_fma_f32 v197, v21, s57, v197
	v_fma_f32 v198, v22, s57, v198
	v_fma_f32 v199, v23, s57, v199
	v_cvt_pk_bf16_f32 v20, v20, v21
	v_cvt_pk_bf16_f32 v21, v22, v23
	s_waitcnt vmcnt(5)
	v_fma_f32 v202, v196, s58, v202
	v_fma_f32 v203, v197, s58, v203
	v_fma_f32 v204, v198, s58, v204
	v_fma_f32 v205, v199, s58, v205
	v_cvt_pk_bf16_f32 v196, v196, v197
	v_cvt_pk_bf16_f32 v197, v198, v199
	s_waitcnt vmcnt(4)
	v_fma_f32 v206, v202, s60, v206
	v_fma_f32 v207, v203, s60, v207
	v_fma_f32 v208, v204, s60, v208
	v_fma_f32 v209, v205, s60, v209
	v_cvt_pk_bf16_f32 v202, v202, v203
	v_cvt_pk_bf16_f32 v203, v204, v205
	s_waitcnt vmcnt(3)
	v_fma_f32 v210, v206, s61, v210
	v_fma_f32 v211, v207, s61, v211
	v_fma_f32 v212, v208, s61, v212
	v_fma_f32 v213, v209, s61, v213
	v_cvt_pk_bf16_f32 v206, v206, v207
	v_cvt_pk_bf16_f32 v207, v208, v209
	s_waitcnt vmcnt(2)
	v_fma_f32 v230, v210, s62, v230
	v_fma_f32 v231, v211, s62, v231
	v_fma_f32 v232, v212, s62, v232
	v_fma_f32 v233, v213, s62, v233
	v_cvt_pk_bf16_f32 v210, v210, v211
	v_cvt_pk_bf16_f32 v211, v212, v213
	s_waitcnt vmcnt(1)
	v_fma_f32 v234, v230, s63, v234
	v_fma_f32 v235, v231, s63, v235
	v_fma_f32 v236, v232, s63, v236
	v_fma_f32 v237, v233, s63, v237
	v_cvt_pk_bf16_f32 v230, v230, v231
	v_cvt_pk_bf16_f32 v231, v232, v233
	s_waitcnt vmcnt(0)
	v_fma_f32 v244, v234, s64, v244
	v_fma_f32 v245, v235, s64, v245
	v_fma_f32 v246, v236, s64, v246
	v_fma_f32 v247, v237, s64, v247
	v_cvt_pk_bf16_f32 v234, v234, v235
	v_cvt_pk_bf16_f32 v235, v236, v237
	global_store_dwordx2 v239, v[214:215], s[10:11]
	s_add_u32 s10, s10, 0x20000
	s_addc_u32 s11, s11, 0
	global_store_dwordx2 v239, v[116:117], s[10:11]
	s_add_u32 s10, s10, 0x20000
	s_addc_u32 s11, s11, 0
	global_store_dwordx2 v239, v[120:121], s[10:11]
	s_add_u32 s10, s10, 0x20000
	s_addc_u32 s11, s11, 0
	global_store_dwordx2 v239, v[124:125], s[10:11]
	s_add_u32 s10, s10, 0x20000
	s_addc_u32 s11, s11, 0
	global_store_dwordx2 v239, v[128:129], s[10:11]
	s_add_u32 s10, s10, 0x20000
	s_addc_u32 s11, s11, 0
	global_store_dwordx2 v239, v[132:133], s[10:11]
	s_add_u32 s10, s10, 0x20000
	s_addc_u32 s11, s11, 0
	global_store_dwordx2 v239, v[136:137], s[10:11]
	s_add_u32 s10, s10, 0x20000
	s_addc_u32 s11, s11, 0
	global_store_dwordx2 v239, v[140:141], s[10:11]
	s_add_u32 s10, s10, 0x20000
	s_addc_u32 s11, s11, 0
	global_store_dwordx2 v239, v[144:145], s[10:11]
	s_add_u32 s10, s10, 0x20000
	s_addc_u32 s11, s11, 0
	global_store_dwordx2 v239, v[148:149], s[10:11]
	s_add_u32 s10, s10, 0x20000
	s_addc_u32 s11, s11, 0
	global_store_dwordx2 v239, v[152:153], s[10:11]
	s_add_u32 s10, s10, 0x20000
	s_addc_u32 s11, s11, 0
	global_store_dwordx2 v239, v[156:157], s[10:11]
	s_add_u32 s10, s10, 0x20000
	s_addc_u32 s11, s11, 0
	global_store_dwordx2 v239, v[160:161], s[10:11]
	s_add_u32 s10, s10, 0x20000
	s_addc_u32 s11, s11, 0
	global_store_dwordx2 v239, v[164:165], s[10:11]
	s_add_u32 s10, s10, 0x20000
	s_addc_u32 s11, s11, 0
	global_store_dwordx2 v239, v[168:169], s[10:11]
	s_add_u32 s10, s10, 0x20000
	s_addc_u32 s11, s11, 0
	global_store_dwordx2 v239, v[172:173], s[10:11]
	s_add_u32 s10, s10, 0x20000
	s_addc_u32 s11, s11, 0
	global_store_dwordx2 v239, v[176:177], s[10:11]
	s_add_u32 s10, s10, 0x20000
	s_addc_u32 s11, s11, 0
	global_store_dwordx2 v239, v[180:181], s[10:11]
	s_add_u32 s10, s10, 0x20000
	s_addc_u32 s11, s11, 0
	global_store_dwordx2 v239, v[184:185], s[10:11]
	s_add_u32 s10, s10, 0x20000
	s_addc_u32 s11, s11, 0
	global_store_dwordx2 v239, v[188:189], s[10:11]
	s_add_u32 s10, s10, 0x20000
	s_addc_u32 s11, s11, 0
	global_store_dwordx2 v239, v[0:1], s[10:11]
	s_add_u32 s10, s10, 0x20000
	s_addc_u32 s11, s11, 0
	global_store_dwordx2 v239, v[4:5], s[10:11]
	s_add_u32 s10, s10, 0x20000
	s_addc_u32 s11, s11, 0
	global_store_dwordx2 v239, v[8:9], s[10:11]
	s_add_u32 s10, s10, 0x20000
	s_addc_u32 s11, s11, 0
	global_store_dwordx2 v239, v[12:13], s[10:11]
	s_add_u32 s10, s10, 0x20000
	s_addc_u32 s11, s11, 0
	global_store_dwordx2 v239, v[16:17], s[10:11]
	s_add_u32 s10, s10, 0x20000
	s_addc_u32 s11, s11, 0
	global_store_dwordx2 v239, v[20:21], s[10:11]
	s_add_u32 s10, s10, 0x20000
	s_addc_u32 s11, s11, 0
	global_store_dwordx2 v239, v[196:197], s[10:11]
	s_add_u32 s10, s10, 0x20000
	s_addc_u32 s11, s11, 0
	global_store_dwordx2 v239, v[202:203], s[10:11]
	s_add_u32 s10, s10, 0x20000
	s_addc_u32 s11, s11, 0
	global_store_dwordx2 v239, v[206:207], s[10:11]
	s_add_u32 s10, s10, 0x20000
	s_addc_u32 s11, s11, 0
	global_store_dwordx2 v239, v[210:211], s[10:11]
	s_add_u32 s10, s10, 0x20000
	s_addc_u32 s11, s11, 0
	global_store_dwordx2 v239, v[230:231], s[10:11]
	s_add_u32 s10, s10, 0x20000
	s_addc_u32 s11, s11, 0
	global_store_dwordx2 v239, v[234:235], s[10:11]
	s_mov_b64 s[4:5], -1
